# P0 balance: phi-bias wave items moved from workgroups 128-143 (which also carry two adaLN tiles) to workgroups 0-15
# speedup vs baseline: 1.0113x; 1.0113x over previous
.LBB0_128:
	s_add_u32 s20, s80, 0x2000
	s_addc_u32 s21, s81, 0
	s_abs_i32 s2, s94
	v_cvt_f32_u32_e32 v2, s2
	s_sub_i32 s5, 0, s2
	s_ashr_i32 s3, s94, 1
	v_rcp_iflag_f32_e32 v2, v2
	s_abs_i32 s4, s12
	s_ashr_i32 s3, s12, 31
	v_mul_f32_e32 v2, 0x4f7ffffe, v2
	v_cvt_u32_f32_e32 v2, v2
	s_nop 0
	v_readfirstlane_b32 s6, v2
	s_mul_i32 s5, s5, s6
	s_mul_hi_u32 s5, s6, s5
	s_add_i32 s6, s6, s5
	s_mul_hi_u32 s5, s4, s6
	s_mul_i32 s5, s5, s2
	s_sub_i32 s4, s4, s5
	s_sub_i32 s5, s4, s2
	s_cmp_ge_u32 s4, s2
	s_cselect_b32 s4, s5, s4
	s_sub_i32 s5, s4, s2
	s_cmp_ge_u32 s4, s2
	s_cselect_b32 s2, s5, s4
	s_xor_b32 s2, s2, s3
	s_sub_i32 s22, s2, s3
	s_cmpk_gt_i32 s22, 0x7f
	s_mov_b32 s3, 0
	s_cbranch_scc1 .LBB0_133
	v_mov_b32_e32 v3, 0
